# census: the 16 XCC counter loads of the first grid barrier issued together; FFN-up unit start no longer drains vmcnt before zeroing accumulators
# baseline (speedup 1.0000x reference)
; template <class Epi, class Sched, bool ALIGN_EPI = false, bool SP2 = false>
; __device__ __forceinline__ void gemm_phase(PG8_LAS unsigned char* lds, const Gemm g, const Sched& S, const Epi& E) {
;     ...
;         const bool has_next = S.next(ui + 1, nxt);
;         const char* nA = has_next ? (const char*)g.A + (size_t)nxt.pm * tstep : cA; const char* nB = has_next ? (const char*)g.Bt + (size_t)nxt.pn * tstep : cB;
;         for (int t = 0; t < nt; t += 2) {
;     ...
; #pragma unroll
;         for (int a = 0; a < 2; ++a)
; #pragma unroll
;             for (int b = 0; b < 2; ++b)
; #pragma unroll
;                 for (int m = 0; m < 4; ++m)
; #pragma unroll
;                     for (int n = 0; n < 2; ++n) acc[a][b][m][n] = (f32x4){0.f, 0.f, 0.f, 0.f};
;         cur = nxt; cA = nA; cB = nB; ++ui;
.LBB0_79:
	s_ashr_i32 s13, s12, 31
	s_lshl_b64 s[6:7], s[12:13], 19
	v_readlane_b32 s4, v252, 41
	s_mov_b32 s38, s12
	v_readlane_b32 s5, v252, 42
	s_add_u32 s4, s4, s6
	v_readlane_b32 s12, v254, 42
	s_addc_u32 s5, s5, s7
	v_readlane_b32 s13, v254, 43
	s_and_b64 s[6:7], s[12:13], exec
	s_cselect_b32 s66, s5, s1
	v_writelane_b32 v254, s4, 50
	s_cselect_b32 s67, s4, s0
	v_mov_b32_e32 v70, 0
	v_writelane_b32 v254, s5, 51
	s_mov_b32 s4, s40
	s_ashr_i32 s5, s40, 31
	s_lshl_b64 s[6:7], s[4:5], 19
	v_readlane_b32 s4, v254, 56
	s_add_u32 s96, s4, s6
	v_readlane_b32 s4, v254, 57
	s_addc_u32 s97, s4, s7
	s_and_b64 s[6:7], s[12:13], exec
	s_cselect_b32 s82, s97, s9
	v_writelane_b32 v254, s96, 48
	s_cselect_b32 s83, s96, s8
	s_mov_b32 vcc_lo, -2
	v_writelane_b32 v254, s97, 49
	s_add_u32 s96, s8, 0x100
	s_addc_u32 s97, s9, 0
	v_mov_b32_e32 v71, v70
	v_mov_b32_e32 v72, v70
	v_mov_b32_e32 v73, v70
	v_mov_b32_e32 v122, v70
	v_mov_b32_e32 v123, v70
	v_mov_b32_e32 v124, v70
	v_mov_b32_e32 v125, v70
	v_mov_b32_e32 v74, v70
	v_mov_b32_e32 v75, v70
	v_mov_b32_e32 v76, v70
	v_mov_b32_e32 v77, v70
	v_mov_b32_e32 v82, v70
	v_mov_b32_e32 v83, v70
	v_mov_b32_e32 v84, v70
	v_mov_b32_e32 v85, v70
	v_mov_b32_e32 v2, v70
	v_mov_b32_e32 v3, v70
	v_mov_b32_e32 v4, v70
	v_mov_b32_e32 v5, v70
	v_mov_b32_e32 v10, v70
	v_mov_b32_e32 v11, v70
	v_mov_b32_e32 v12, v70
	v_mov_b32_e32 v13, v70
	v_mov_b32_e32 v50, v70
	v_mov_b32_e32 v51, v70
	v_mov_b32_e32 v52, v70
	v_mov_b32_e32 v53, v70
	v_mov_b32_e32 v114, v70
	v_mov_b32_e32 v115, v70
	v_mov_b32_e32 v116, v70
	v_mov_b32_e32 v117, v70
	v_mov_b32_e32 v66, v70
	v_mov_b32_e32 v67, v70
	v_mov_b32_e32 v68, v70
	v_mov_b32_e32 v69, v70
	v_mov_b32_e32 v126, v70
	v_mov_b32_e32 v127, v70
	v_mov_b32_e32 v128, v70
	v_mov_b32_e32 v129, v70
	v_mov_b32_e32 v86, v70
	v_mov_b32_e32 v87, v70
	v_mov_b32_e32 v88, v70
	v_mov_b32_e32 v89, v70
	v_mov_b32_e32 v90, v70
	v_mov_b32_e32 v91, v70
	v_mov_b32_e32 v92, v70
	v_mov_b32_e32 v93, v70
	v_mov_b32_e32 v6, v70
	v_mov_b32_e32 v7, v70
	v_mov_b32_e32 v8, v70
	v_mov_b32_e32 v9, v70
	v_mov_b32_e32 v14, v70
	v_mov_b32_e32 v15, v70
	v_mov_b32_e32 v16, v70
	v_mov_b32_e32 v17, v70
	v_mov_b32_e32 v46, v70
	v_mov_b32_e32 v47, v70
	v_mov_b32_e32 v48, v70
	v_mov_b32_e32 v49, v70
	v_mov_b32_e32 v106, v70
	v_mov_b32_e32 v107, v70
	v_mov_b32_e32 v108, v70
	v_mov_b32_e32 v109, v70
	v_mov_b32_e32 v62, v70
	v_mov_b32_e32 v63, v70
	v_mov_b32_e32 v64, v70
	v_mov_b32_e32 v65, v70
	v_mov_b32_e32 v78, v70
	v_mov_b32_e32 v79, v70
	v_mov_b32_e32 v80, v70
	v_mov_b32_e32 v81, v70
	v_mov_b32_e32 v26, v70
	v_mov_b32_e32 v27, v70
	v_mov_b32_e32 v28, v70
	v_mov_b32_e32 v29, v70
	v_mov_b32_e32 v42, v70
	v_mov_b32_e32 v43, v70
	v_mov_b32_e32 v44, v70
	v_mov_b32_e32 v45, v70
	v_mov_b32_e32 v98, v70
	v_mov_b32_e32 v99, v70
	v_mov_b32_e32 v100, v70
	v_mov_b32_e32 v101, v70
	v_mov_b32_e32 v102, v70
	v_mov_b32_e32 v103, v70
	v_mov_b32_e32 v104, v70
	v_mov_b32_e32 v105, v70
	v_mov_b32_e32 v138, v70
	v_mov_b32_e32 v139, v70
	v_mov_b32_e32 v140, v70
	v_mov_b32_e32 v141, v70
	v_mov_b32_e32 v142, v70
	v_mov_b32_e32 v143, v70
	v_mov_b32_e32 v144, v70
	v_mov_b32_e32 v145, v70
	v_mov_b32_e32 v58, v70
	v_mov_b32_e32 v59, v70
	v_mov_b32_e32 v60, v70
	v_mov_b32_e32 v61, v70
	v_mov_b32_e32 v94, v70
	v_mov_b32_e32 v95, v70
	v_mov_b32_e32 v96, v70
	v_mov_b32_e32 v97, v70
	v_mov_b32_e32 v30, v70
	v_mov_b32_e32 v31, v70
	v_mov_b32_e32 v32, v70
	v_mov_b32_e32 v33, v70
	v_mov_b32_e32 v54, v70
	v_mov_b32_e32 v55, v70
	v_mov_b32_e32 v56, v70
	v_mov_b32_e32 v57, v70
	v_mov_b32_e32 v110, v70
	v_mov_b32_e32 v111, v70
	v_mov_b32_e32 v112, v70
	v_mov_b32_e32 v113, v70
	v_mov_b32_e32 v118, v70
	v_mov_b32_e32 v119, v70
	v_mov_b32_e32 v120, v70
	v_mov_b32_e32 v121, v70
	v_mov_b32_e32 v146, v70
	v_mov_b32_e32 v147, v70
	v_mov_b32_e32 v148, v70
	v_mov_b32_e32 v149, v70
	v_mov_b32_e32 v150, v70
	v_mov_b32_e32 v151, v70
	v_mov_b32_e32 v152, v70
	v_mov_b32_e32 v153, v70

; __device__ __forceinline__ unsigned xb_ld(unsigned* p)              { return __hip_atomic_load(p, __ATOMIC_RELAXED, __HIP_MEMORY_SCOPE_AGENT); }
; __device__ __forceinline__ void xcd_barrier_complete(unsigned* bar, unsigned x, unsigned& nloc, unsigned& nx) {
;     ...
;     for (;;) {
;         sum = 0u; cnt = 0u; mine = 0u;
; #pragma unroll
;         for (unsigned j = 0; j < 16; ++j) { const unsigned c = xb_ld(&bar[XB_XCNT(j)]); sum += c; cnt += (c > 0u) ? 1u : 0u; mine = (j == x) ? c : mine; }
;         if (sum == G) break;
;         __builtin_amdgcn_s_sleep(1);
;         if ((++sp & 255u) == 0u) { if (xb_ld(&bar[XB_TMO])) break; if (sp > XB_SPIN_CAP) { atomicAdd(&bar[XB_TMO], 1u); break; } }
;     }
.LBB0_488:
	v_readlane_b32 s4, v253, 26
	v_readlane_b32 s5, v253, 27
	s_mov_b64 s[6:7], -1
	s_nop 4
	global_load_dword v0, v1, s[4:5] sc1
	v_readlane_b32 s4, v253, 28
	v_readlane_b32 s5, v253, 29
	s_nop 4
	global_load_dword v2, v1, s[4:5] sc1
	v_readlane_b32 s4, v253, 30
	v_readlane_b32 s5, v253, 31
	s_nop 4
	global_load_dword v3, v1, s[4:5] sc1
	v_readlane_b32 s4, v253, 32
	v_readlane_b32 s5, v253, 33
	s_nop 4
	global_load_dword v4, v1, s[4:5] sc1
	v_readlane_b32 s4, v253, 34
	v_readlane_b32 s5, v253, 35
	s_nop 4
	global_load_dword v5, v1, s[4:5] sc1
	v_readlane_b32 s4, v253, 36
	v_readlane_b32 s5, v253, 37
	s_nop 4
	global_load_dword v6, v1, s[4:5] sc1
	v_readlane_b32 s4, v253, 38
	v_readlane_b32 s5, v253, 39
	s_nop 4
	global_load_dword v7, v1, s[4:5] sc1
	v_readlane_b32 s4, v253, 40
	v_readlane_b32 s5, v253, 41
	s_nop 4
	global_load_dword v8, v1, s[4:5] sc1
	v_readlane_b32 s4, v253, 42
	v_readlane_b32 s5, v253, 43
	s_nop 4
	global_load_dword v9, v1, s[4:5] sc1
	v_readlane_b32 s4, v253, 44
	v_readlane_b32 s5, v253, 45
	s_nop 4
	global_load_dword v10, v1, s[4:5] sc1
	v_readlane_b32 s4, v253, 46
	v_readlane_b32 s5, v253, 47
	s_nop 4
	global_load_dword v11, v1, s[4:5] sc1
	v_readlane_b32 s4, v253, 48
	v_readlane_b32 s5, v253, 49
	s_nop 4
	global_load_dword v12, v1, s[4:5] sc1
	v_readlane_b32 s4, v253, 50
	v_readlane_b32 s5, v253, 51
	s_nop 4
	global_load_dword v13, v1, s[4:5] sc1
	v_readlane_b32 s4, v253, 52
	v_readlane_b32 s5, v253, 53
	s_nop 4
	global_load_dword v14, v1, s[4:5] sc1
	v_readlane_b32 s4, v253, 54
	v_readlane_b32 s5, v253, 55
	s_nop 4
	global_load_dword v15, v1, s[4:5] sc1
	v_readlane_b32 s4, v253, 56
	v_readlane_b32 s5, v253, 57
	s_nop 4
	global_load_dword v16, v1, s[4:5] sc1
	s_mov_b64 s[4:5], -1
	s_waitcnt vmcnt(0)
	v_add_u32_e32 v17, v2, v0
	v_add_u32_e32 v17, v17, v3
	v_add_u32_e32 v17, v17, v4
	v_add_u32_e32 v17, v17, v5
	v_add_u32_e32 v17, v17, v6
	v_add_u32_e32 v17, v17, v7
	v_add_u32_e32 v17, v17, v8
	v_add_u32_e32 v17, v17, v9
	v_add_u32_e32 v17, v17, v10
	v_add_u32_e32 v17, v17, v11
	v_add_u32_e32 v17, v17, v12
	v_add_u32_e32 v17, v17, v13
	v_add_u32_e32 v17, v17, v14
	v_add_u32_e32 v17, v17, v15
	v_add_u32_e32 v17, v17, v16
	v_cmp_eq_u32_e32 vcc, s10, v17
	s_cbranch_vccnz .LBB0_487
	s_and_b32 s4, s11, 0xff
	s_cmp_eq_u32 s4, 0
	s_mov_b64 s[4:5], -1
	s_mov_b64 s[8:9], -1
	s_sleep 1
	s_cbranch_scc0 .LBB0_492
	v_readlane_b32 s4, v253, 24
	v_readlane_b32 s5, v253, 25
	s_nop 4
	global_load_dword v17, v1, s[4:5] sc1
	s_waitcnt vmcnt(0)
	v_cmp_eq_u32_e32 vcc, 0, v17
	s_cbranch_vccnz .LBB0_494
	s_mov_b64 s[8:9], 0
	s_mov_b64 s[4:5], -1
